# packed v_pk_mul_f32 in the S1 GEMM silu epilogue split into scalar v_mul_f32 (packed fp32 ops are slow on this chip)
# baseline (speedup 1.0000x reference)
.LBB0_325:
	v_add_u32_e32 v66, v78, v153
	ds_read_b128 v[66:69], v66
	s_and_saveexec_b64 s[4:5], vcc
	s_cbranch_execz .LBB0_327
	s_waitcnt lgkmcnt(0)
	v_mul_f32_e32 v71, 0xbfb8aa3b, v66
	v_exp_f32_e32 v71, v71
	v_mul_f32_e32 v81, 0xbfb8aa3b, v68
	v_mul_f32_e32 v79, 0xbfb8aa3b, v67
	v_exp_f32_e32 v79, v79
	v_add_f32_e32 v71, 1.0, v71
	v_rcp_f32_e32 v80, v71
	v_exp_f32_e32 v71, v81
	v_mul_f32_e32 v81, 0xbfb8aa3b, v69
	v_exp_f32_e32 v81, v81
	v_add_f32_e32 v79, 1.0, v79
	v_add_f32_e32 v71, 1.0, v71
	v_rcp_f32_e32 v82, v71
	v_add_f32_e32 v71, 1.0, v81
	v_rcp_f32_e32 v83, v71
	v_rcp_f32_e32 v81, v79
	v_mul_f32_e32 v68, v68, v82
	v_mul_f32_e32 v69, v69, v83
	v_mul_f32_e32 v66, v66, v80
	v_mul_f32_e32 v67, v67, v81
.LBB0_327:
	s_or_b64 exec, exec, s[4:5]
	v_add_u32_e32 v80, -12, v70
	v_ashrrev_i32_e32 v81, 31, v80
	s_waitcnt lgkmcnt(0)
	v_cvt_pk_bf16_f32 v66, v66, v67
	v_cvt_pk_bf16_f32 v67, v68, v69
	v_lshlrev_b64 v[68:69], 13, v[80:81]
	v_lshl_add_u64 v[68:69], v[132:133], 0, v[68:69]
	global_store_dwordx2 v[68:69], v[66:67], off
	v_add_u32_e32 v66, v78, v75
	ds_read_b128 v[66:69], v66 offset:1024
	s_and_saveexec_b64 s[4:5], vcc
	s_cbranch_execz .LBB0_329
	s_waitcnt lgkmcnt(0)
	v_mul_f32_e32 v71, 0xbfb8aa3b, v66
	v_exp_f32_e32 v71, v71
	v_mul_f32_e32 v81, 0xbfb8aa3b, v68
	v_mul_f32_e32 v79, 0xbfb8aa3b, v67
	v_exp_f32_e32 v79, v79
	v_add_f32_e32 v71, 1.0, v71
	v_rcp_f32_e32 v80, v71
	v_exp_f32_e32 v71, v81
	v_mul_f32_e32 v81, 0xbfb8aa3b, v69
	v_exp_f32_e32 v81, v81
	v_add_f32_e32 v79, 1.0, v79
	v_add_f32_e32 v71, 1.0, v71
	v_rcp_f32_e32 v82, v71
	v_add_f32_e32 v71, 1.0, v81
	v_rcp_f32_e32 v83, v71
	v_rcp_f32_e32 v81, v79
	v_mul_f32_e32 v68, v68, v82
	v_mul_f32_e32 v69, v69, v83
	v_mul_f32_e32 v66, v66, v80
	v_mul_f32_e32 v67, v67, v81
.LBB0_329:
	s_or_b64 exec, exec, s[4:5]
	v_add_u32_e32 v80, -8, v70
	v_ashrrev_i32_e32 v81, 31, v80
	s_waitcnt lgkmcnt(0)
	v_cvt_pk_bf16_f32 v66, v66, v67
	v_cvt_pk_bf16_f32 v67, v68, v69
	v_lshlrev_b64 v[68:69], 13, v[80:81]
	v_lshl_add_u64 v[68:69], v[132:133], 0, v[68:69]
	global_store_dwordx2 v[68:69], v[66:67], off
	v_add_u32_e32 v66, v78, v74
	ds_read_b128 v[66:69], v66 offset:2048
	s_and_saveexec_b64 s[4:5], vcc
	s_cbranch_execz .LBB0_331
	s_waitcnt lgkmcnt(0)
	v_mul_f32_e32 v71, 0xbfb8aa3b, v66
	v_exp_f32_e32 v71, v71
	v_mul_f32_e32 v81, 0xbfb8aa3b, v68
	v_mul_f32_e32 v79, 0xbfb8aa3b, v67
	v_exp_f32_e32 v79, v79
	v_add_f32_e32 v71, 1.0, v71
	v_rcp_f32_e32 v80, v71
	v_exp_f32_e32 v71, v81
	v_mul_f32_e32 v81, 0xbfb8aa3b, v69
	v_exp_f32_e32 v81, v81
	v_add_f32_e32 v79, 1.0, v79
	v_add_f32_e32 v71, 1.0, v71
	v_rcp_f32_e32 v82, v71
	v_add_f32_e32 v71, 1.0, v81
	v_rcp_f32_e32 v83, v71
	v_rcp_f32_e32 v81, v79
	v_mul_f32_e32 v68, v68, v82
	v_mul_f32_e32 v69, v69, v83
	v_mul_f32_e32 v66, v66, v80
	v_mul_f32_e32 v67, v67, v81
.LBB0_331:
	s_or_b64 exec, exec, s[4:5]
	v_add_u32_e32 v80, -4, v70
	v_ashrrev_i32_e32 v81, 31, v80
	s_waitcnt lgkmcnt(0)
	v_cvt_pk_bf16_f32 v66, v66, v67
	v_cvt_pk_bf16_f32 v67, v68, v69
	v_lshlrev_b64 v[68:69], 13, v[80:81]
	v_lshl_add_u64 v[68:69], v[132:133], 0, v[68:69]
	global_store_dwordx2 v[68:69], v[66:67], off
	v_add_u32_e32 v66, v78, v72
	ds_read_b128 v[66:69], v66 offset:3072
	s_and_saveexec_b64 s[4:5], vcc
	s_cbranch_execz .LBB0_324
	s_waitcnt lgkmcnt(0)
	v_mul_f32_e32 v71, 0xbfb8aa3b, v66
	v_exp_f32_e32 v71, v71
	v_mul_f32_e32 v81, 0xbfb8aa3b, v68
	v_mul_f32_e32 v79, 0xbfb8aa3b, v67
	v_exp_f32_e32 v79, v79
	v_add_f32_e32 v71, 1.0, v71
	v_rcp_f32_e32 v80, v71
	v_exp_f32_e32 v71, v81
	v_mul_f32_e32 v81, 0xbfb8aa3b, v69
	v_exp_f32_e32 v81, v81
	v_add_f32_e32 v79, 1.0, v79
	v_add_f32_e32 v71, 1.0, v71
	v_rcp_f32_e32 v82, v71
	v_add_f32_e32 v71, 1.0, v81
	v_rcp_f32_e32 v83, v71
	v_rcp_f32_e32 v81, v79
	v_mul_f32_e32 v68, v68, v82
	v_mul_f32_e32 v69, v69, v83
	v_mul_f32_e32 v66, v66, v80
	v_mul_f32_e32 v67, v67, v81
	s_branch .LBB0_324

.LBB0_335:
	v_add_u32_e32 v2, v73, v153
	ds_read_b128 v[2:5], v2
	s_and_saveexec_b64 s[2:3], vcc
	s_cbranch_execz .LBB0_337
	s_waitcnt lgkmcnt(0)
	v_mul_f32_e32 v7, 0xbfb8aa3b, v2
	v_exp_f32_e32 v7, v7
	v_mul_f32_e32 v8, 0xbfb8aa3b, v3
	v_mul_f32_e32 v9, 0xbfb8aa3b, v4
	v_exp_f32_e32 v10, v8
	v_add_f32_e32 v7, 1.0, v7
	v_rcp_f32_e32 v8, v7
	v_exp_f32_e32 v7, v9
	v_mul_f32_e32 v9, 0xbfb8aa3b, v5
	v_exp_f32_e32 v9, v9
	v_add_f32_e32 v12, 1.0, v10
	v_add_f32_e32 v7, 1.0, v7
	v_rcp_f32_e32 v10, v7
	v_add_f32_e32 v7, 1.0, v9
	v_rcp_f32_e32 v11, v7
	v_rcp_f32_e32 v9, v12
	v_mul_f32_e32 v4, v4, v10
	v_mul_f32_e32 v5, v5, v11
	v_mul_f32_e32 v2, v2, v8
	v_mul_f32_e32 v3, v3, v9
.LBB0_337:
	s_or_b64 exec, exec, s[2:3]
	v_add_u32_e32 v8, -12, v6
	v_ashrrev_i32_e32 v9, 31, v8
	s_waitcnt lgkmcnt(0)
	v_cvt_pk_bf16_f32 v2, v2, v3
	v_cvt_pk_bf16_f32 v3, v4, v5
	v_lshlrev_b64 v[4:5], 13, v[8:9]
	v_lshl_add_u64 v[4:5], v[132:133], 0, v[4:5]
	global_store_dwordx2 v[4:5], v[2:3], off
	v_add_u32_e32 v2, v73, v75
	ds_read_b128 v[2:5], v2 offset:1024
	s_and_saveexec_b64 s[2:3], vcc
	s_cbranch_execz .LBB0_339
	s_waitcnt lgkmcnt(0)
	v_mul_f32_e32 v7, 0xbfb8aa3b, v2
	v_exp_f32_e32 v7, v7
	v_mul_f32_e32 v8, 0xbfb8aa3b, v3
	v_mul_f32_e32 v9, 0xbfb8aa3b, v4
	v_exp_f32_e32 v10, v8
	v_add_f32_e32 v7, 1.0, v7
	v_rcp_f32_e32 v8, v7
	v_exp_f32_e32 v7, v9
	v_mul_f32_e32 v9, 0xbfb8aa3b, v5
	v_exp_f32_e32 v9, v9
	v_add_f32_e32 v12, 1.0, v10
	v_add_f32_e32 v7, 1.0, v7
	v_rcp_f32_e32 v10, v7
	v_add_f32_e32 v7, 1.0, v9
	v_rcp_f32_e32 v11, v7
	v_rcp_f32_e32 v9, v12
	v_mul_f32_e32 v4, v4, v10
	v_mul_f32_e32 v5, v5, v11
	v_mul_f32_e32 v2, v2, v8
	v_mul_f32_e32 v3, v3, v9
.LBB0_339:
	s_or_b64 exec, exec, s[2:3]
	v_add_u32_e32 v8, -8, v6
	v_ashrrev_i32_e32 v9, 31, v8
	s_waitcnt lgkmcnt(0)
	v_cvt_pk_bf16_f32 v2, v2, v3
	v_cvt_pk_bf16_f32 v3, v4, v5
	v_lshlrev_b64 v[4:5], 13, v[8:9]
	v_lshl_add_u64 v[4:5], v[132:133], 0, v[4:5]
	global_store_dwordx2 v[4:5], v[2:3], off
	v_add_u32_e32 v2, v73, v74
	ds_read_b128 v[2:5], v2 offset:2048
	s_and_saveexec_b64 s[2:3], vcc
	s_cbranch_execz .LBB0_341
	s_waitcnt lgkmcnt(0)
	v_mul_f32_e32 v7, 0xbfb8aa3b, v2
	v_exp_f32_e32 v7, v7
	v_mul_f32_e32 v8, 0xbfb8aa3b, v3
	v_mul_f32_e32 v9, 0xbfb8aa3b, v4
	v_exp_f32_e32 v10, v8
	v_add_f32_e32 v7, 1.0, v7
	v_rcp_f32_e32 v8, v7
	v_exp_f32_e32 v7, v9
	v_mul_f32_e32 v9, 0xbfb8aa3b, v5
	v_exp_f32_e32 v9, v9
	v_add_f32_e32 v12, 1.0, v10
	v_add_f32_e32 v7, 1.0, v7
	v_rcp_f32_e32 v10, v7
	v_add_f32_e32 v7, 1.0, v9
	v_rcp_f32_e32 v11, v7
	v_rcp_f32_e32 v9, v12
	v_mul_f32_e32 v4, v4, v10
	v_mul_f32_e32 v5, v5, v11
	v_mul_f32_e32 v2, v2, v8
	v_mul_f32_e32 v3, v3, v9
.LBB0_341:
	s_or_b64 exec, exec, s[2:3]
	v_add_u32_e32 v8, -4, v6
	v_ashrrev_i32_e32 v9, 31, v8
	s_waitcnt lgkmcnt(0)
	v_cvt_pk_bf16_f32 v2, v2, v3
	v_cvt_pk_bf16_f32 v3, v4, v5
	v_lshlrev_b64 v[4:5], 13, v[8:9]
	v_lshl_add_u64 v[4:5], v[132:133], 0, v[4:5]
	global_store_dwordx2 v[4:5], v[2:3], off
	v_add_u32_e32 v2, v73, v72
	ds_read_b128 v[2:5], v2 offset:3072
	s_and_saveexec_b64 s[2:3], vcc
	s_cbranch_execz .LBB0_334
	s_waitcnt lgkmcnt(0)
	v_mul_f32_e32 v7, 0xbfb8aa3b, v2
	v_exp_f32_e32 v7, v7
	v_mul_f32_e32 v8, 0xbfb8aa3b, v3
	v_mul_f32_e32 v9, 0xbfb8aa3b, v4
	v_exp_f32_e32 v10, v8
	v_add_f32_e32 v7, 1.0, v7
	v_rcp_f32_e32 v8, v7
	v_exp_f32_e32 v7, v9
	v_mul_f32_e32 v9, 0xbfb8aa3b, v5
	v_exp_f32_e32 v9, v9
	v_add_f32_e32 v12, 1.0, v10
	v_add_f32_e32 v7, 1.0, v7
	v_rcp_f32_e32 v10, v7
	v_add_f32_e32 v7, 1.0, v9
	v_rcp_f32_e32 v11, v7
	v_rcp_f32_e32 v9, v12
	v_mul_f32_e32 v4, v4, v10
	v_mul_f32_e32 v5, v5, v11
	v_mul_f32_e32 v2, v2, v8
	v_mul_f32_e32 v3, v3, v9
	s_branch .LBB0_334
